# indexer pass 2: hand-written collect body, slot atomics of the 4 tiles batched behind one wait
# baseline (speedup 1.0000x reference)
; DI void dsa_task(const Params& p, int l, int isP, int b, int tq, char* smem, const bool dry) {
;     ...
;             } else if (kind == 1) {
;               const unsigned hk = key >> 16;
;               const bool tz = (hk == prefix) && ((key & 0xFFFFu) == 0u);
;               if (hk > prefix) {
;                 const unsigned slot = atomicAdd(&cnt[qloc], 1u);
;                 if (slot < 256u) idxl[qloc * 256 + slot] = (unsigned short)kidx;
;               } else if (hk == prefix && !tz) {
;                 const unsigned c = atomicAdd(&ccnt[qloc], 1u);
;                 if (c < 64u) { ckey[qloc * 64 + c] = key; cidx[qloc * 64 + c] = (unsigned)kidx; }
;               }
;               const unsigned long long bm = __ballot(tz);
;               if (bm != 0ull) {
;                 const unsigned mg = (unsigned)(bm >> (g4 * 16)) & 0xFFFFu;
;                 const unsigned rank = tiecnt + __popc(mg & ((1u << cl) - 1u));
;                 if (tz && rank < need) tiel[qloc * 256 + rank] = (unsigned short)kidx;
;                 tiecnt += __popc(mg);
;               }
.Lidx_k1:
	s_nop 1
	v_max_f32_e32 v224, 0, v60
	v_max_f32_e32 v228, 0, v56
	v_max_f32_e32 v225, 0, v61
	v_max_f32_e32 v229, 0, v57
	v_max_f32_e32 v226, 0, v62
	v_max_f32_e32 v230, 0, v58
	v_max_f32_e32 v227, 0, v63
	v_max_f32_e32 v231, 0, v59
	v_mul_f32_e32 v225, v13, v225
	v_mul_f32_e32 v229, v13, v229
	v_fmac_f32_e32 v225, v12, v224
	v_fmac_f32_e32 v229, v12, v228
	v_fmac_f32_e32 v225, v14, v226
	v_fmac_f32_e32 v229, v14, v230
	v_fmac_f32_e32 v225, v15, v227
	v_fmac_f32_e32 v229, v15, v231
	v_add_f32_e32 v224, 0, v225
	v_add_f32_e32 v228, 0, v229
	v_ashrrev_i32_e32 v225, 31, v224
	v_ashrrev_i32_e32 v229, 31, v228
	v_bitop3_b32 v226, v225, v224, s71 bitop3:0x36
	v_bitop3_b32 v230, v229, v228, s71 bitop3:0x36
	v_lshrrev_b32_e32 v224, 16, v226
	v_lshrrev_b32_e32 v228, 16, v230
	v_max_f32_e32 v232, 0, v52
	v_max_f32_e32 v236, 0, v48
	v_max_f32_e32 v233, 0, v53
	v_max_f32_e32 v237, 0, v49
	v_max_f32_e32 v234, 0, v54
	v_max_f32_e32 v238, 0, v50
	v_max_f32_e32 v235, 0, v55
	v_max_f32_e32 v239, 0, v51
	v_mul_f32_e32 v233, v13, v233
	v_mul_f32_e32 v237, v13, v237
	v_fmac_f32_e32 v233, v12, v232
	v_fmac_f32_e32 v237, v12, v236
	v_fmac_f32_e32 v233, v14, v234
	v_fmac_f32_e32 v237, v14, v238
	v_fmac_f32_e32 v233, v15, v235
	v_fmac_f32_e32 v237, v15, v239
	v_add_f32_e32 v232, 0, v233
	v_add_f32_e32 v236, 0, v237
	v_ashrrev_i32_e32 v233, 31, v232
	v_ashrrev_i32_e32 v237, 31, v236
	v_bitop3_b32 v234, v233, v232, s71 bitop3:0x36
	v_bitop3_b32 v238, v237, v236, s71 bitop3:0x36
	v_lshrrev_b32_e32 v232, 16, v234
	v_lshrrev_b32_e32 v236, 16, v238
	v_add_u32_e32 v231, 16, v122
	v_add_u32_e32 v235, 32, v122
	v_add_u32_e32 v239, 48, v122
	v_cmp_gt_u32_e64 s[38:39], v224, v101
	v_cmp_gt_u32_e64 s[40:41], v228, v101
	v_cmp_gt_u32_e64 s[42:43], v232, v101
	v_cmp_gt_u32_e64 s[82:83], v236, v101
	s_mov_b64 s[98:99], exec
	s_mov_b64 exec, s[38:39]
	ds_add_rtn_u32 v225, v84, v185 offset:61440
	s_mov_b64 exec, s[40:41]
	ds_add_rtn_u32 v229, v84, v185 offset:61440
	s_mov_b64 exec, s[42:43]
	ds_add_rtn_u32 v233, v84, v185 offset:61440
	s_mov_b64 exec, s[82:83]
	ds_add_rtn_u32 v237, v84, v185 offset:61440
	s_mov_b64 exec, s[98:99]
	v_cmp_eq_u32_e64 s[100:101], v224, v101
	v_cmp_eq_u32_e32 vcc, v228, v101
	s_or_b64 s[100:101], s[100:101], vcc
	v_cmp_eq_u32_e32 vcc, v232, v101
	s_or_b64 s[100:101], s[100:101], vcc
	v_cmp_eq_u32_e32 vcc, v236, v101
	s_or_b64 s[100:101], s[100:101], vcc
	s_waitcnt lgkmcnt(0)
	s_mov_b64 exec, s[38:39]
	v_cmp_gt_u32_e32 vcc, s90, v225
	s_and_b64 exec, exec, vcc
	v_lshl_add_u32 v225, v225, 1, v87
	ds_write_b16 v225, v122 offset:16384
	s_mov_b64 exec, s[40:41]
	v_cmp_gt_u32_e32 vcc, s90, v229
	s_and_b64 exec, exec, vcc
	v_lshl_add_u32 v229, v229, 1, v87
	ds_write_b16 v229, v231 offset:16384
	s_mov_b64 exec, s[42:43]
	v_cmp_gt_u32_e32 vcc, s90, v233
	s_and_b64 exec, exec, vcc
	v_lshl_add_u32 v233, v233, 1, v87
	ds_write_b16 v233, v235 offset:16384
	s_mov_b64 exec, s[82:83]
	v_cmp_gt_u32_e32 vcc, s90, v237
	s_and_b64 exec, exec, vcc
	v_lshl_add_u32 v237, v237, 1, v87
	ds_write_b16 v237, v239 offset:16384
	s_mov_b64 exec, s[98:99]
	s_cmp_lg_u64 s[100:101], 0
	s_cbranch_scc1 .Lk1_rare
	s_branch .LBB0_1310
.Lk1_rare:
	v_cmp_eq_u32_e64 s[38:39], v224, v101
	s_cmp_lg_u64 s[38:39], 0
	s_cbranch_scc0 .Lk1_r0_end
	v_and_b32_e32 v240, 0xffff, v226
	v_cmp_eq_u32_e64 s[40:41], 0, v240
	s_and_b64 s[42:43], s[38:39], s[40:41]
	s_andn2_b64 s[38:39], s[38:39], s[40:41]
	s_cmp_lg_u64 s[38:39], 0
	s_cbranch_scc0 .Lk1_c0_end
	s_mov_b64 exec, s[38:39]
	ds_add_rtn_u32 v241, v84, v185 offset:61632
	s_waitcnt lgkmcnt(0)
	v_cmp_gt_u32_e32 vcc, 64, v241
	s_and_b64 exec, exec, vcc
	v_or_b32_e32 v241, v241, v85
	v_lshlrev_b32_e32 v241, 2, v241
	v_add_u32_e32 v242, 0x10200, v241
	ds_write_b32 v241, v226 offset:61952
	ds_write_b32 v242, v122
	s_mov_b64 exec, s[98:99]
; DI void dsa_task(const Params& p, int l, int isP, int b, int tq, char* smem, const bool dry) {
;     ...
;             } else if (kind == 1) {
;               const unsigned hk = key >> 16;
;               const bool tz = (hk == prefix) && ((key & 0xFFFFu) == 0u);
;               if (hk > prefix) {
;                 const unsigned slot = atomicAdd(&cnt[qloc], 1u);
;                 if (slot < 256u) idxl[qloc * 256 + slot] = (unsigned short)kidx;
;               } else if (hk == prefix && !tz) {
;                 const unsigned c = atomicAdd(&ccnt[qloc], 1u);
;                 if (c < 64u) { ckey[qloc * 64 + c] = key; cidx[qloc * 64 + c] = (unsigned)kidx; }
;               }
;               const unsigned long long bm = __ballot(tz);
;               if (bm != 0ull) {
;                 const unsigned mg = (unsigned)(bm >> (g4 * 16)) & 0xFFFFu;
;                 const unsigned rank = tiecnt + __popc(mg & ((1u << cl) - 1u));
;                 if (tz && rank < need) tiel[qloc * 256 + rank] = (unsigned short)kidx;
;                 tiecnt += __popc(mg);
;               }
.Lk1_c0_end:
	s_cmp_lg_u64 s[42:43], 0
	s_cbranch_scc0 .Lk1_r0_end
	v_lshrrev_b64 v[244:245], v86, s[42:43]
	v_and_b32_e32 v240, v244, v90
	v_bcnt_u32_b32 v240, v240, v121
	v_cmp_lt_u32_e32 vcc, v240, v117
	s_and_b64 exec, s[42:43], vcc
	v_lshl_add_u32 v240, v240, 1, v87
	ds_write_b16 v240, v122
	s_mov_b64 exec, s[98:99]
	v_and_b32_e32 v244, 0xffff, v244
	v_bcnt_u32_b32 v121, v244, v121
.Lk1_r0_end:
	v_cmp_eq_u32_e64 s[38:39], v228, v101
	s_cmp_lg_u64 s[38:39], 0
	s_cbranch_scc0 .Lk1_r1_end
	v_and_b32_e32 v240, 0xffff, v230
	v_cmp_eq_u32_e64 s[40:41], 0, v240
	s_and_b64 s[42:43], s[38:39], s[40:41]
	s_andn2_b64 s[38:39], s[38:39], s[40:41]
	s_cmp_lg_u64 s[38:39], 0
	s_cbranch_scc0 .Lk1_c1_end
	s_mov_b64 exec, s[38:39]
	ds_add_rtn_u32 v241, v84, v185 offset:61632
	s_waitcnt lgkmcnt(0)
	v_cmp_gt_u32_e32 vcc, 64, v241
	s_and_b64 exec, exec, vcc
	v_or_b32_e32 v241, v241, v85
	v_lshlrev_b32_e32 v241, 2, v241
	v_add_u32_e32 v242, 0x10200, v241
	ds_write_b32 v241, v230 offset:61952
	ds_write_b32 v242, v231
	s_mov_b64 exec, s[98:99]
.Lk1_c1_end:
	s_cmp_lg_u64 s[42:43], 0
	s_cbranch_scc0 .Lk1_r1_end
	v_lshrrev_b64 v[244:245], v86, s[42:43]
	v_and_b32_e32 v240, v244, v90
	v_bcnt_u32_b32 v240, v240, v121
	v_cmp_lt_u32_e32 vcc, v240, v117
	s_and_b64 exec, s[42:43], vcc
	v_lshl_add_u32 v240, v240, 1, v87
	ds_write_b16 v240, v231
	s_mov_b64 exec, s[98:99]
	v_and_b32_e32 v244, 0xffff, v244
	v_bcnt_u32_b32 v121, v244, v121
.Lk1_r1_end:
	v_cmp_eq_u32_e64 s[38:39], v232, v101
	s_cmp_lg_u64 s[38:39], 0
	s_cbranch_scc0 .Lk1_r2_end
	v_and_b32_e32 v240, 0xffff, v234
	v_cmp_eq_u32_e64 s[40:41], 0, v240
	s_and_b64 s[42:43], s[38:39], s[40:41]
	s_andn2_b64 s[38:39], s[38:39], s[40:41]
	s_cmp_lg_u64 s[38:39], 0
	s_cbranch_scc0 .Lk1_c2_end
	s_mov_b64 exec, s[38:39]
	ds_add_rtn_u32 v241, v84, v185 offset:61632
	s_waitcnt lgkmcnt(0)
	v_cmp_gt_u32_e32 vcc, 64, v241
	s_and_b64 exec, exec, vcc
	v_or_b32_e32 v241, v241, v85
	v_lshlrev_b32_e32 v241, 2, v241
	v_add_u32_e32 v242, 0x10200, v241
	ds_write_b32 v241, v234 offset:61952
	ds_write_b32 v242, v235
	s_mov_b64 exec, s[98:99]
.Lk1_c2_end:
	s_cmp_lg_u64 s[42:43], 0
	s_cbranch_scc0 .Lk1_r2_end
	v_lshrrev_b64 v[244:245], v86, s[42:43]
	v_and_b32_e32 v240, v244, v90
	v_bcnt_u32_b32 v240, v240, v121
	v_cmp_lt_u32_e32 vcc, v240, v117
	s_and_b64 exec, s[42:43], vcc
	v_lshl_add_u32 v240, v240, 1, v87
	ds_write_b16 v240, v235
	s_mov_b64 exec, s[98:99]
	v_and_b32_e32 v244, 0xffff, v244
	v_bcnt_u32_b32 v121, v244, v121
.Lk1_r2_end:
	v_cmp_eq_u32_e64 s[38:39], v236, v101
	s_cmp_lg_u64 s[38:39], 0
	s_cbranch_scc0 .Lk1_r3_end
	v_and_b32_e32 v240, 0xffff, v238
	v_cmp_eq_u32_e64 s[40:41], 0, v240
	s_and_b64 s[42:43], s[38:39], s[40:41]
	s_andn2_b64 s[38:39], s[38:39], s[40:41]
	s_cmp_lg_u64 s[38:39], 0
	s_cbranch_scc0 .Lk1_c3_end
	s_mov_b64 exec, s[38:39]
	ds_add_rtn_u32 v241, v84, v185 offset:61632
	s_waitcnt lgkmcnt(0)
	v_cmp_gt_u32_e32 vcc, 64, v241
	s_and_b64 exec, exec, vcc
	v_or_b32_e32 v241, v241, v85
	v_lshlrev_b32_e32 v241, 2, v241
	v_add_u32_e32 v242, 0x10200, v241
	ds_write_b32 v241, v238 offset:61952
	ds_write_b32 v242, v239
	s_mov_b64 exec, s[98:99]
.Lk1_c3_end:
	s_cmp_lg_u64 s[42:43], 0
	s_cbranch_scc0 .Lk1_r3_end
	v_lshrrev_b64 v[244:245], v86, s[42:43]
	v_and_b32_e32 v240, v244, v90
	v_bcnt_u32_b32 v240, v240, v121
	v_cmp_lt_u32_e32 vcc, v240, v117
	s_and_b64 exec, s[42:43], vcc
	v_lshl_add_u32 v240, v240, 1, v87
	ds_write_b16 v240, v239
	s_mov_b64 exec, s[98:99]
	v_and_b32_e32 v244, 0xffff, v244
	v_bcnt_u32_b32 v121, v244, v121
.Lk1_r3_end:
	s_branch .LBB0_1310
.LBB0_1307:
	s_or_b64 exec, exec, s[38:39]
	v_and_b32_e32 v48, 0xffff, v48
	v_bcnt_u32_b32 v121, v48, v121

; DI f32x4 mfma16(bf16x8 a, bf16x8 b, f32x4 c) { return __builtin_amdgcn_mfma_f32_16x16x32_bf16(a, b, c, 0, 0, 0); }
; DI float relu_(float x) { return __builtin_amdgcn_fmed3f(x, 0.f, __builtin_inff()); }
; DI void dsa_task(const Params& p, int l, int isP, int b, int tq, char* smem, const bool dry) {
;     ...
;         for (int tg = 0; tg < ngrp; tg++) {
;           unsigned keys[4];
; #pragma unroll
;           for (int tt = 0; tt < 4; tt++) {
;             const bf16_t* br = kst + ((tg * 4 + tt) * 16 + cl) * 72 + g4 * 8;
;             const bf16x8 b0 = *(const bf16x8*)br;
;             const bf16x8 b1 = *(const bf16x8*)(br + 32);
;             f32x4 a = (f32x4){0.f, 0.f, 0.f, 0.f};
;             a = mfma16(aq0, b0, a);
;             a = mfma16(aq1, b1, a);
;             const float score = wq.x * relu_(a[0]) + wq.y * relu_(a[1]) + wq.z * relu_(a[2]) + wq.w * relu_(a[3]);
;             keys[tt] = mono_key(score);
;           }
; #pragma unroll
;           for (int tt = 0; tt < 4; tt++) {
;             const unsigned key = keys[tt];
;             const int kidx = kc * 256 + (tg * 4 + tt) * 16 + cl;
;             if (kind == 0) {
;               const bool match = (pass == 0) || ((key >> (shift + 8)) == prefix);
;               if (match) atomicAdd(&hist[qloc * 256 + ((key >> shift) & 255u)], 1u);
;             } else if (kind == 1) {
.LBB0_1311:
	ds_read_b128 v[224:227], v123
	ds_read_b128 v[228:231], v123 offset:64
	ds_read_b128 v[232:235], v123 offset:2304
	ds_read_b128 v[236:239], v123 offset:2368
	ds_read_b128 v[240:243], v123 offset:4608
	ds_read_b128 v[244:247], v123 offset:4672
	ds_read_b128 v[248:251], v123 offset:6912
	ds_read_b128 v[124:127], v123 offset:6976
	s_cmp_lt_i32 s76, 5
	s_waitcnt lgkmcnt(7)
	v_mfma_f32_16x16x32_bf16 v[60:63], v[4:7], v[224:227], 0
	s_waitcnt lgkmcnt(5)
	v_mfma_f32_16x16x32_bf16 v[56:59], v[4:7], v[232:235], 0
	s_waitcnt lgkmcnt(3)
	v_mfma_f32_16x16x32_bf16 v[52:55], v[4:7], v[240:243], 0
	s_waitcnt lgkmcnt(1)
	v_mfma_f32_16x16x32_bf16 v[48:51], v[4:7], v[248:251], 0
	v_mfma_f32_16x16x32_bf16 v[60:63], v[8:11], v[228:231], v[60:63]
	v_mfma_f32_16x16x32_bf16 v[56:59], v[8:11], v[236:239], v[56:59]
	v_mfma_f32_16x16x32_bf16 v[52:55], v[8:11], v[244:247], v[52:55]
	s_waitcnt lgkmcnt(0)
	v_mfma_f32_16x16x32_bf16 v[48:51], v[8:11], v[124:127], v[48:51]
	s_cmp_lt_u32 s76, 2
	s_cbranch_scc1 .Lidx_k0
	s_cmp_eq_u32 s76, 2
	s_cbranch_scc1 .Lidx_k1
	s_cmp_lt_i32 s76, 5
	s_cbranch_scc1 .LBB0_1313
	s_cmp_lg_u32 s76, 5
	s_mov_b64 s[38:39], -1
	s_cselect_b64 s[40:41], -1, 0
	s_cbranch_execz .LBB0_1314
	s_branch .LBB0_1315

; __global__ void __launch_bounds__(256, 2) mega(Params pk) {
;   const Params& p = *(const Params*)__builtin_amdgcn_kernarg_segment_ptr();
;   cg::grid_group grid = cg::this_grid();
;   __shared__ __attribute__((aligned(16))) char smem[SMEM];
	.amdhsa_kernel _Z4mega6Params
		.amdhsa_group_segment_fixed_size 73728
		.amdhsa_private_segment_fixed_size 0
		.amdhsa_kernarg_size 696
		.amdhsa_user_sgpr_count 2
		.amdhsa_user_sgpr_dispatch_ptr 0
		.amdhsa_user_sgpr_queue_ptr 0
		.amdhsa_user_sgpr_kernarg_segment_ptr 1
		.amdhsa_user_sgpr_dispatch_id 0
		.amdhsa_user_sgpr_kernarg_preload_length 0
		.amdhsa_user_sgpr_kernarg_preload_offset 0
		.amdhsa_user_sgpr_private_segment_size 0
		.amdhsa_uses_dynamic_stack 0
		.amdhsa_enable_private_segment 0
		.amdhsa_system_sgpr_workgroup_id_x 1
		.amdhsa_system_sgpr_workgroup_id_y 0
		.amdhsa_system_sgpr_workgroup_id_z 0
		.amdhsa_system_sgpr_workgroup_info 0
		.amdhsa_system_vgpr_workitem_id 2
		.amdhsa_next_free_vgpr 256
		.amdhsa_next_free_sgpr 102
		.amdhsa_accum_offset 256
		.amdhsa_reserve_vcc 1
		.amdhsa_float_round_mode_32 0
		.amdhsa_float_round_mode_16_64 0
		.amdhsa_float_denorm_mode_32 3
		.amdhsa_float_denorm_mode_16_64 3
		.amdhsa_dx10_clamp 1
		.amdhsa_ieee_mode 1
		.amdhsa_fp16_overflow 0
		.amdhsa_tg_split 0
		.amdhsa_exception_fp_ieee_invalid_op 0
		.amdhsa_exception_fp_denorm_src 0
		.amdhsa_exception_fp_ieee_div_zero 0
		.amdhsa_exception_fp_ieee_overflow 0
		.amdhsa_exception_fp_ieee_underflow 0
		.amdhsa_exception_fp_ieee_inexact 0
		.amdhsa_exception_int_div_zero 0
	.end_amdhsa_kernel

; __global__ void __launch_bounds__(256, 2) mega(Params pk) {
;   const Params& p = *(const Params*)__builtin_amdgcn_kernarg_segment_ptr();
;   cg::grid_group grid = cg::this_grid();
;   __shared__ __attribute__((aligned(16))) char smem[SMEM];
amdhsa.kernels:
  - .agpr_count:     0
    .args:
      - .offset:         0
        .size:           440
        .value_kind:     by_value
      - .offset:         440
        .size:           4
        .value_kind:     hidden_block_count_x
      - .offset:         444
        .size:           4
        .value_kind:     hidden_block_count_y
      - .offset:         448
        .size:           4
        .value_kind:     hidden_block_count_z
      - .offset:         452
        .size:           2
        .value_kind:     hidden_group_size_x
      - .offset:         454
        .size:           2
        .value_kind:     hidden_group_size_y
      - .offset:         456
        .size:           2
        .value_kind:     hidden_group_size_z
      - .offset:         458
        .size:           2
        .value_kind:     hidden_remainder_x
      - .offset:         460
        .size:           2
        .value_kind:     hidden_remainder_y
      - .offset:         462
        .size:           2
        .value_kind:     hidden_remainder_z
      - .offset:         480
        .size:           8
        .value_kind:     hidden_global_offset_x
      - .offset:         488
        .size:           8
        .value_kind:     hidden_global_offset_y
      - .offset:         496
        .size:           8
        .value_kind:     hidden_global_offset_z
      - .offset:         504
        .size:           2
        .value_kind:     hidden_grid_dims
      - .offset:         528
        .size:           8
        .value_kind:     hidden_multigrid_sync_arg
    .group_segment_fixed_size: 73728
    .kernarg_segment_align: 8
    .kernarg_segment_size: 696
    .language:       OpenCL C
    .language_version:
      - 2
      - 0
    .max_flat_workgroup_size: 256
    .name:           _Z4mega6Params
    .private_segment_fixed_size: 0
    .sgpr_count:     108
    .sgpr_spill_count: 76
    .symbol:         _Z4mega6Params.kd
    .uniform_work_group_size: 1
    .uses_dynamic_stack: false
    .vgpr_count:     256
    .vgpr_spill_count: 0
    .wavefront_size: 64
